# hand-written residual epilogue (EK_RES): residual loads of a tile issued together under counted waits instead of one vmcnt(0) per load
# speedup vs baseline: 1.1077x; 1.0218x over previous
.LBB0_321:
	s_andn2_b64 vcc, exec, s[0:1]
	s_cbranch_vccnz .LBB0_611
	v_lshlrev_b32_e32 v172, 12, v164
	v_lshl_or_b32 v173, s72, 8, v181
	v_lshlrev_b32_e32 v174, 2, v164
	v_cmp_lt_i32_e32 vcc, v230, v228
	v_lshl_add_u32 v172, v173, 2, v172
	v_readlane_b32 s2, v255, 36
	v_cndmask_b32_e32 v175, v226, v230, vcc
	v_cmp_lt_i32_e32 vcc, v229, v228
	v_readlane_b32 s3, v255, 37
	v_lshrrev_b32_e32 v173, 1, v172
	v_cndmask_b32_e32 v176, v226, v229, vcc
	v_lshlrev_b32_e32 v175, 2, v175
	v_lshlrev_b32_e32 v176, 2, v176
	s_cmp_lg_u64 s[94:95], 0
	s_cselect_b32 s43, 1, 0
	s_cmp_lg_u64 s[2:3], 0
	s_cselect_b32 s44, 1, 0
	s_cmp_lg_u64 s[92:93], 0
	s_cbranch_scc0 .Ler_bf
	v_add_u32_e32 v177, 0x0, v172
	global_load_dwordx4 v[184:187], v177, s[92:93]
	global_load_dwordx4 v[188:191], v177, s[92:93] offset:64
	global_load_dwordx4 v[192:195], v177, s[92:93] offset:512
	global_load_dwordx4 v[196:199], v177, s[92:93] offset:576
	v_add_u32_e32 v177, 0x10000, v172
	global_load_dwordx4 v[200:203], v177, s[92:93]
	global_load_dwordx4 v[204:207], v177, s[92:93] offset:64
	global_load_dwordx4 v[208:211], v177, s[92:93] offset:512
	global_load_dwordx4 v[212:215], v177, s[92:93] offset:576
	v_add_u32_e32 v177, 0x20000, v172
	global_load_dwordx4 v[216:219], v177, s[92:93]
	global_load_dwordx4 v[220:223], v177, s[92:93] offset:64
	global_load_dwordx4 v[128:131], v177, s[92:93] offset:512
	global_load_dwordx4 v[132:135], v177, s[92:93] offset:576
	v_add_u32_e32 v177, 0x30000, v172
	global_load_dwordx4 v[136:139], v177, s[92:93]
	global_load_dwordx4 v[140:143], v177, s[92:93] offset:64
	global_load_dwordx4 v[164:167], v177, s[92:93] offset:512
	global_load_dwordx4 v[168:171], v177, s[92:93] offset:576
	s_waitcnt vmcnt(12)
	v_add_f32_e32 v124, v124, v184
	v_add_f32_e32 v125, v125, v185
	v_add_f32_e32 v126, v126, v186
	v_add_f32_e32 v127, v127, v187
	v_add_f32_e32 v120, v120, v188
	v_add_f32_e32 v121, v121, v189
	v_add_f32_e32 v122, v122, v190
	v_add_f32_e32 v123, v123, v191
	v_add_f32_e32 v92, v92, v192
	v_add_f32_e32 v93, v93, v193
	v_add_f32_e32 v94, v94, v194
	v_add_f32_e32 v95, v95, v195
	v_add_f32_e32 v88, v88, v196
	v_add_f32_e32 v89, v89, v197
	v_add_f32_e32 v90, v90, v198
	v_add_f32_e32 v91, v91, v199
	s_cmp_eq_u32 s43, 0
	s_cbranch_scc1 .Ler_f0_b
	v_add_u32_e32 v177, 0x0, v172
	global_store_dwordx4 v177, v[124:127], s[94:95]
	global_store_dwordx4 v177, v[120:123], s[94:95] offset:64
	global_store_dwordx4 v177, v[92:95], s[94:95] offset:512
	global_store_dwordx4 v177, v[88:91], s[94:95] offset:576
	s_branch .Ler_f0_o
.Ler_f0_b:
	v_add_u32_e32 v177, 0x0, v173
	v_cvt_pk_bf16_f32 v184, v124, v125
	v_cvt_pk_bf16_f32 v185, v126, v127
	v_cvt_pk_bf16_f32 v188, v120, v121
	v_cvt_pk_bf16_f32 v189, v122, v123
	v_cvt_pk_bf16_f32 v192, v92, v93
	v_cvt_pk_bf16_f32 v193, v94, v95
	v_cvt_pk_bf16_f32 v196, v88, v89
	v_cvt_pk_bf16_f32 v197, v90, v91
	global_store_dwordx2 v177, v[184:185], s[48:49]
	global_store_dwordx2 v177, v[188:189], s[48:49] offset:32
	global_store_dwordx2 v177, v[192:193], s[48:49] offset:256
	global_store_dwordx2 v177, v[196:197], s[48:49] offset:288
.Ler_f0_o:
	s_cmp_eq_u32 s44, 0
	s_cbranch_scc1 .Ler_f0_n
	v_mul_f32_e32 v245, v124, v124
	v_mul_f32_e32 v246, v125, v125
	v_add_f32_e32 v236, v245, v246
	v_mul_f32_e32 v245, v126, v126
	v_mul_f32_e32 v246, v127, v127
	v_add_f32_e32 v236, v245, v236
	v_add_f32_e32 v236, v246, v236
	v_mul_f32_e32 v245, v120, v120
	v_mul_f32_e32 v246, v121, v121
	v_add_f32_e32 v237, v245, v246
	v_mul_f32_e32 v245, v122, v122
	v_mul_f32_e32 v246, v123, v123
	v_add_f32_e32 v237, v245, v237
	v_add_f32_e32 v237, v246, v237
	v_add_f32_e32 v244, v236, v237
	v_mul_f32_e32 v245, v92, v92
	v_mul_f32_e32 v246, v93, v93
	v_add_f32_e32 v236, v245, v246
	v_mul_f32_e32 v245, v94, v94
	v_mul_f32_e32 v246, v95, v95
	v_add_f32_e32 v236, v245, v236
	v_add_f32_e32 v236, v246, v236
	v_add_f32_e32 v244, v244, v236
	v_mul_f32_e32 v245, v88, v88
	v_mul_f32_e32 v246, v89, v89
	v_add_f32_e32 v237, v245, v246
	v_mul_f32_e32 v245, v90, v90
	v_mul_f32_e32 v246, v91, v91
	v_add_f32_e32 v237, v245, v237
	v_add_f32_e32 v237, v246, v237
	v_add_f32_e32 v244, v244, v237
	ds_bpermute_b32 v247, v175, v244
	s_waitcnt lgkmcnt(0)
	v_add_f32_e32 v244, v244, v247
	ds_bpermute_b32 v247, v176, v244
	s_waitcnt lgkmcnt(0)
	s_and_saveexec_b64 s[0:1], s[36:37]
	v_add_f32_e32 v244, v244, v247
	global_atomic_add_f32 v174, v244, s[2:3]
	s_mov_b64 exec, s[0:1]
.Ler_f0_n:
	v_add_u32_e32 v177, 0x80000, v172
	global_load_dwordx4 v[184:187], v177, s[92:93]
	global_load_dwordx4 v[188:191], v177, s[92:93] offset:64
	global_load_dwordx4 v[192:195], v177, s[92:93] offset:512
	global_load_dwordx4 v[196:199], v177, s[92:93] offset:576
	s_waitcnt vmcnt(16)
	v_add_f32_e32 v116, v116, v200
	v_add_f32_e32 v117, v117, v201
	v_add_f32_e32 v118, v118, v202
	v_add_f32_e32 v119, v119, v203
	v_add_f32_e32 v112, v112, v204
	v_add_f32_e32 v113, v113, v205
	v_add_f32_e32 v114, v114, v206
	v_add_f32_e32 v115, v115, v207
	v_add_f32_e32 v84, v84, v208
	v_add_f32_e32 v85, v85, v209
	v_add_f32_e32 v86, v86, v210
	v_add_f32_e32 v87, v87, v211
	v_add_f32_e32 v80, v80, v212
	v_add_f32_e32 v81, v81, v213
	v_add_f32_e32 v82, v82, v214
	v_add_f32_e32 v83, v83, v215
	s_cmp_eq_u32 s43, 0
	s_cbranch_scc1 .Ler_f1_b
	v_add_u32_e32 v177, 0x10000, v172
	global_store_dwordx4 v177, v[116:119], s[94:95]
	global_store_dwordx4 v177, v[112:115], s[94:95] offset:64
	global_store_dwordx4 v177, v[84:87], s[94:95] offset:512
	global_store_dwordx4 v177, v[80:83], s[94:95] offset:576
	s_branch .Ler_f1_o
.Ler_f1_b:
	v_add_u32_e32 v177, 0x8000, v173
	v_cvt_pk_bf16_f32 v200, v116, v117
	v_cvt_pk_bf16_f32 v201, v118, v119
	v_cvt_pk_bf16_f32 v204, v112, v113
	v_cvt_pk_bf16_f32 v205, v114, v115
	v_cvt_pk_bf16_f32 v208, v84, v85
	v_cvt_pk_bf16_f32 v209, v86, v87
	v_cvt_pk_bf16_f32 v212, v80, v81
	v_cvt_pk_bf16_f32 v213, v82, v83
	global_store_dwordx2 v177, v[200:201], s[48:49]
	global_store_dwordx2 v177, v[204:205], s[48:49] offset:32
	global_store_dwordx2 v177, v[208:209], s[48:49] offset:256
	global_store_dwordx2 v177, v[212:213], s[48:49] offset:288
.Ler_f1_o:
	s_cmp_eq_u32 s44, 0
	s_cbranch_scc1 .Ler_f1_n
	v_mul_f32_e32 v245, v116, v116
	v_mul_f32_e32 v246, v117, v117
	v_add_f32_e32 v236, v245, v246
	v_mul_f32_e32 v245, v118, v118
	v_mul_f32_e32 v246, v119, v119
	v_add_f32_e32 v236, v245, v236
	v_add_f32_e32 v236, v246, v236
	v_mul_f32_e32 v245, v112, v112
	v_mul_f32_e32 v246, v113, v113
	v_add_f32_e32 v237, v245, v246
	v_mul_f32_e32 v245, v114, v114
	v_mul_f32_e32 v246, v115, v115
	v_add_f32_e32 v237, v245, v237
	v_add_f32_e32 v237, v246, v237
	v_add_f32_e32 v244, v236, v237
	v_mul_f32_e32 v245, v84, v84
	v_mul_f32_e32 v246, v85, v85
	v_add_f32_e32 v236, v245, v246
	v_mul_f32_e32 v245, v86, v86
	v_mul_f32_e32 v246, v87, v87
	v_add_f32_e32 v236, v245, v236
	v_add_f32_e32 v236, v246, v236
	v_add_f32_e32 v244, v244, v236
	v_mul_f32_e32 v245, v80, v80
	v_mul_f32_e32 v246, v81, v81
	v_add_f32_e32 v237, v245, v246
	v_mul_f32_e32 v245, v82, v82
	v_mul_f32_e32 v246, v83, v83
	v_add_f32_e32 v237, v245, v237
	v_add_f32_e32 v237, v246, v237
	v_add_f32_e32 v244, v244, v237
	ds_bpermute_b32 v247, v175, v244
	s_waitcnt lgkmcnt(0)
	v_add_f32_e32 v244, v244, v247
	ds_bpermute_b32 v247, v176, v244
	s_waitcnt lgkmcnt(0)
	s_and_saveexec_b64 s[0:1], s[36:37]
	v_add_f32_e32 v244, v244, v247
	global_atomic_add_f32 v174, v244, s[2:3] offset:64
	s_mov_b64 exec, s[0:1]
.Ler_f1_n:
	v_add_u32_e32 v177, 0x90000, v172
	global_load_dwordx4 v[200:203], v177, s[92:93]
	global_load_dwordx4 v[204:207], v177, s[92:93] offset:64
	global_load_dwordx4 v[208:211], v177, s[92:93] offset:512
	global_load_dwordx4 v[212:215], v177, s[92:93] offset:576
	s_waitcnt vmcnt(20)
	v_add_f32_e32 v108, v108, v216
	v_add_f32_e32 v109, v109, v217
	v_add_f32_e32 v110, v110, v218
	v_add_f32_e32 v111, v111, v219
	v_add_f32_e32 v104, v104, v220
	v_add_f32_e32 v105, v105, v221
	v_add_f32_e32 v106, v106, v222
	v_add_f32_e32 v107, v107, v223
	v_add_f32_e32 v76, v76, v128
	v_add_f32_e32 v77, v77, v129
	v_add_f32_e32 v78, v78, v130
	v_add_f32_e32 v79, v79, v131
	v_add_f32_e32 v72, v72, v132
	v_add_f32_e32 v73, v73, v133
	v_add_f32_e32 v74, v74, v134
	v_add_f32_e32 v75, v75, v135
	s_cmp_eq_u32 s43, 0
	s_cbranch_scc1 .Ler_f2_b
	v_add_u32_e32 v177, 0x20000, v172
	global_store_dwordx4 v177, v[108:111], s[94:95]
	global_store_dwordx4 v177, v[104:107], s[94:95] offset:64
	global_store_dwordx4 v177, v[76:79], s[94:95] offset:512
	global_store_dwordx4 v177, v[72:75], s[94:95] offset:576
	s_branch .Ler_f2_o
.Ler_f2_b:
	v_add_u32_e32 v177, 0x10000, v173
	v_cvt_pk_bf16_f32 v216, v108, v109
	v_cvt_pk_bf16_f32 v217, v110, v111
	v_cvt_pk_bf16_f32 v220, v104, v105
	v_cvt_pk_bf16_f32 v221, v106, v107
	v_cvt_pk_bf16_f32 v128, v76, v77
	v_cvt_pk_bf16_f32 v129, v78, v79
	v_cvt_pk_bf16_f32 v132, v72, v73
	v_cvt_pk_bf16_f32 v133, v74, v75
	global_store_dwordx2 v177, v[216:217], s[48:49]
	global_store_dwordx2 v177, v[220:221], s[48:49] offset:32
	global_store_dwordx2 v177, v[128:129], s[48:49] offset:256
	global_store_dwordx2 v177, v[132:133], s[48:49] offset:288
.Ler_f2_o:
	s_cmp_eq_u32 s44, 0
	s_cbranch_scc1 .Ler_f2_n
	v_mul_f32_e32 v245, v108, v108
	v_mul_f32_e32 v246, v109, v109
	v_add_f32_e32 v236, v245, v246
	v_mul_f32_e32 v245, v110, v110
	v_mul_f32_e32 v246, v111, v111
	v_add_f32_e32 v236, v245, v236
	v_add_f32_e32 v236, v246, v236
	v_mul_f32_e32 v245, v104, v104
	v_mul_f32_e32 v246, v105, v105
	v_add_f32_e32 v237, v245, v246
	v_mul_f32_e32 v245, v106, v106
	v_mul_f32_e32 v246, v107, v107
	v_add_f32_e32 v237, v245, v237
	v_add_f32_e32 v237, v246, v237
	v_add_f32_e32 v244, v236, v237
	v_mul_f32_e32 v245, v76, v76
	v_mul_f32_e32 v246, v77, v77
	v_add_f32_e32 v236, v245, v246
	v_mul_f32_e32 v245, v78, v78
	v_mul_f32_e32 v246, v79, v79
	v_add_f32_e32 v236, v245, v236
	v_add_f32_e32 v236, v246, v236
	v_add_f32_e32 v244, v244, v236
	v_mul_f32_e32 v245, v72, v72
	v_mul_f32_e32 v246, v73, v73
	v_add_f32_e32 v237, v245, v246
	v_mul_f32_e32 v245, v74, v74
	v_mul_f32_e32 v246, v75, v75
	v_add_f32_e32 v237, v245, v237
	v_add_f32_e32 v237, v246, v237
	v_add_f32_e32 v244, v244, v237
	ds_bpermute_b32 v247, v175, v244
	s_waitcnt lgkmcnt(0)
	v_add_f32_e32 v244, v244, v247
	ds_bpermute_b32 v247, v176, v244
	s_waitcnt lgkmcnt(0)
	s_and_saveexec_b64 s[0:1], s[36:37]
	v_add_f32_e32 v244, v244, v247
	global_atomic_add_f32 v174, v244, s[2:3] offset:128
	s_mov_b64 exec, s[0:1]
.Ler_f2_n:
	v_add_u32_e32 v177, 0xa0000, v172
	global_load_dwordx4 v[216:219], v177, s[92:93]
	global_load_dwordx4 v[220:223], v177, s[92:93] offset:64
	global_load_dwordx4 v[128:131], v177, s[92:93] offset:512
	global_load_dwordx4 v[132:135], v177, s[92:93] offset:576
	s_waitcnt vmcnt(24)
	v_add_f32_e32 v100, v100, v136
	v_add_f32_e32 v101, v101, v137
	v_add_f32_e32 v102, v102, v138
	v_add_f32_e32 v103, v103, v139
	v_add_f32_e32 v96, v96, v140
	v_add_f32_e32 v97, v97, v141
	v_add_f32_e32 v98, v98, v142
	v_add_f32_e32 v99, v99, v143
	v_add_f32_e32 v68, v68, v164
	v_add_f32_e32 v69, v69, v165
	v_add_f32_e32 v70, v70, v166
	v_add_f32_e32 v71, v71, v167
	v_add_f32_e32 v64, v64, v168
	v_add_f32_e32 v65, v65, v169
	v_add_f32_e32 v66, v66, v170
	v_add_f32_e32 v67, v67, v171
	s_cmp_eq_u32 s43, 0
	s_cbranch_scc1 .Ler_f3_b
	v_add_u32_e32 v177, 0x30000, v172
	global_store_dwordx4 v177, v[100:103], s[94:95]
	global_store_dwordx4 v177, v[96:99], s[94:95] offset:64
	global_store_dwordx4 v177, v[68:71], s[94:95] offset:512
	global_store_dwordx4 v177, v[64:67], s[94:95] offset:576
	s_branch .Ler_f3_o
.Ler_f3_b:
	v_add_u32_e32 v177, 0x18000, v173
	v_cvt_pk_bf16_f32 v136, v100, v101
	v_cvt_pk_bf16_f32 v137, v102, v103
	v_cvt_pk_bf16_f32 v140, v96, v97
	v_cvt_pk_bf16_f32 v141, v98, v99
	v_cvt_pk_bf16_f32 v164, v68, v69
	v_cvt_pk_bf16_f32 v165, v70, v71
	v_cvt_pk_bf16_f32 v168, v64, v65
	v_cvt_pk_bf16_f32 v169, v66, v67
	global_store_dwordx2 v177, v[136:137], s[48:49]
	global_store_dwordx2 v177, v[140:141], s[48:49] offset:32
	global_store_dwordx2 v177, v[164:165], s[48:49] offset:256
	global_store_dwordx2 v177, v[168:169], s[48:49] offset:288
.Ler_f3_o:
	s_cmp_eq_u32 s44, 0
	s_cbranch_scc1 .Ler_f3_n
	v_mul_f32_e32 v245, v100, v100
	v_mul_f32_e32 v246, v101, v101
	v_add_f32_e32 v236, v245, v246
	v_mul_f32_e32 v245, v102, v102
	v_mul_f32_e32 v246, v103, v103
	v_add_f32_e32 v236, v245, v236
	v_add_f32_e32 v236, v246, v236
	v_mul_f32_e32 v245, v96, v96
	v_mul_f32_e32 v246, v97, v97
	v_add_f32_e32 v237, v245, v246
	v_mul_f32_e32 v245, v98, v98
	v_mul_f32_e32 v246, v99, v99
	v_add_f32_e32 v237, v245, v237
	v_add_f32_e32 v237, v246, v237
	v_add_f32_e32 v244, v236, v237
	v_mul_f32_e32 v245, v68, v68
	v_mul_f32_e32 v246, v69, v69
	v_add_f32_e32 v236, v245, v246
	v_mul_f32_e32 v245, v70, v70
	v_mul_f32_e32 v246, v71, v71
	v_add_f32_e32 v236, v245, v236
	v_add_f32_e32 v236, v246, v236
	v_add_f32_e32 v244, v244, v236
	v_mul_f32_e32 v245, v64, v64
	v_mul_f32_e32 v246, v65, v65
	v_add_f32_e32 v237, v245, v246
	v_mul_f32_e32 v245, v66, v66
	v_mul_f32_e32 v246, v67, v67
	v_add_f32_e32 v237, v245, v237
	v_add_f32_e32 v237, v246, v237
	v_add_f32_e32 v244, v244, v237
	ds_bpermute_b32 v247, v175, v244
	s_waitcnt lgkmcnt(0)
	v_add_f32_e32 v244, v244, v247
	ds_bpermute_b32 v247, v176, v244
	s_waitcnt lgkmcnt(0)
	s_and_saveexec_b64 s[0:1], s[36:37]
	v_add_f32_e32 v244, v244, v247
	global_atomic_add_f32 v174, v244, s[2:3] offset:192
	s_mov_b64 exec, s[0:1]
.Ler_f3_n:
	v_add_u32_e32 v177, 0xb0000, v172
	global_load_dwordx4 v[136:139], v177, s[92:93]
	global_load_dwordx4 v[140:143], v177, s[92:93] offset:64
	global_load_dwordx4 v[164:167], v177, s[92:93] offset:512
	global_load_dwordx4 v[168:171], v177, s[92:93] offset:576
	s_waitcnt vmcnt(24)
	v_add_f32_e32 v60, v60, v184
	v_add_f32_e32 v61, v61, v185
	v_add_f32_e32 v62, v62, v186
	v_add_f32_e32 v63, v63, v187
	v_add_f32_e32 v56, v56, v188
	v_add_f32_e32 v57, v57, v189
	v_add_f32_e32 v58, v58, v190
	v_add_f32_e32 v59, v59, v191
	v_add_f32_e32 v28, v28, v192
	v_add_f32_e32 v29, v29, v193
	v_add_f32_e32 v30, v30, v194
	v_add_f32_e32 v31, v31, v195
	v_add_f32_e32 v24, v24, v196
	v_add_f32_e32 v25, v25, v197
	v_add_f32_e32 v26, v26, v198
	v_add_f32_e32 v27, v27, v199
	s_cmp_eq_u32 s43, 0
	s_cbranch_scc1 .Ler_f4_b
	v_add_u32_e32 v177, 0x80000, v172
	global_store_dwordx4 v177, v[60:63], s[94:95]
	global_store_dwordx4 v177, v[56:59], s[94:95] offset:64
	global_store_dwordx4 v177, v[28:31], s[94:95] offset:512
	global_store_dwordx4 v177, v[24:27], s[94:95] offset:576
	s_branch .Ler_f4_o
.Ler_f4_b:
	v_add_u32_e32 v177, 0x40000, v173
	v_cvt_pk_bf16_f32 v184, v60, v61
	v_cvt_pk_bf16_f32 v185, v62, v63
	v_cvt_pk_bf16_f32 v188, v56, v57
	v_cvt_pk_bf16_f32 v189, v58, v59
	v_cvt_pk_bf16_f32 v192, v28, v29
	v_cvt_pk_bf16_f32 v193, v30, v31
	v_cvt_pk_bf16_f32 v196, v24, v25
	v_cvt_pk_bf16_f32 v197, v26, v27
	global_store_dwordx2 v177, v[184:185], s[48:49]
	global_store_dwordx2 v177, v[188:189], s[48:49] offset:32
	global_store_dwordx2 v177, v[192:193], s[48:49] offset:256
	global_store_dwordx2 v177, v[196:197], s[48:49] offset:288
.Ler_f4_o:
	s_cmp_eq_u32 s44, 0
	s_cbranch_scc1 .Ler_f4_n
	v_mul_f32_e32 v245, v60, v60
	v_mul_f32_e32 v246, v61, v61
	v_add_f32_e32 v236, v245, v246
	v_mul_f32_e32 v245, v62, v62
	v_mul_f32_e32 v246, v63, v63
	v_add_f32_e32 v236, v245, v236
	v_add_f32_e32 v236, v246, v236
	v_mul_f32_e32 v245, v56, v56
	v_mul_f32_e32 v246, v57, v57
	v_add_f32_e32 v237, v245, v246
	v_mul_f32_e32 v245, v58, v58
	v_mul_f32_e32 v246, v59, v59
	v_add_f32_e32 v237, v245, v237
	v_add_f32_e32 v237, v246, v237
	v_add_f32_e32 v244, v236, v237
	v_mul_f32_e32 v245, v28, v28
	v_mul_f32_e32 v246, v29, v29
	v_add_f32_e32 v236, v245, v246
	v_mul_f32_e32 v245, v30, v30
	v_mul_f32_e32 v246, v31, v31
	v_add_f32_e32 v236, v245, v236
	v_add_f32_e32 v236, v246, v236
	v_add_f32_e32 v244, v244, v236
	v_mul_f32_e32 v245, v24, v24
	v_mul_f32_e32 v246, v25, v25
	v_add_f32_e32 v237, v245, v246
	v_mul_f32_e32 v245, v26, v26
	v_mul_f32_e32 v246, v27, v27
	v_add_f32_e32 v237, v245, v237
	v_add_f32_e32 v237, v246, v237
	v_add_f32_e32 v244, v244, v237
	ds_bpermute_b32 v247, v175, v244
	s_waitcnt lgkmcnt(0)
	v_add_f32_e32 v244, v244, v247
	ds_bpermute_b32 v247, v176, v244
	s_waitcnt lgkmcnt(0)
	s_and_saveexec_b64 s[0:1], s[36:37]
	v_add_f32_e32 v244, v244, v247
	global_atomic_add_f32 v174, v244, s[2:3] offset:512
	s_mov_b64 exec, s[0:1]
.Ler_f4_n:
	s_waitcnt vmcnt(20)
	v_add_f32_e32 v52, v52, v200
	v_add_f32_e32 v53, v53, v201
	v_add_f32_e32 v54, v54, v202
	v_add_f32_e32 v55, v55, v203
	v_add_f32_e32 v48, v48, v204
	v_add_f32_e32 v49, v49, v205
	v_add_f32_e32 v50, v50, v206
	v_add_f32_e32 v51, v51, v207
	v_add_f32_e32 v20, v20, v208
	v_add_f32_e32 v21, v21, v209
	v_add_f32_e32 v22, v22, v210
	v_add_f32_e32 v23, v23, v211
	v_add_f32_e32 v16, v16, v212
	v_add_f32_e32 v17, v17, v213
	v_add_f32_e32 v18, v18, v214
	v_add_f32_e32 v19, v19, v215
	s_cmp_eq_u32 s43, 0
	s_cbranch_scc1 .Ler_f5_b
	v_add_u32_e32 v177, 0x90000, v172
	global_store_dwordx4 v177, v[52:55], s[94:95]
	global_store_dwordx4 v177, v[48:51], s[94:95] offset:64
	global_store_dwordx4 v177, v[20:23], s[94:95] offset:512
	global_store_dwordx4 v177, v[16:19], s[94:95] offset:576
	s_branch .Ler_f5_o
.Ler_f5_b:
	v_add_u32_e32 v177, 0x48000, v173
	v_cvt_pk_bf16_f32 v200, v52, v53
	v_cvt_pk_bf16_f32 v201, v54, v55
	v_cvt_pk_bf16_f32 v204, v48, v49
	v_cvt_pk_bf16_f32 v205, v50, v51
	v_cvt_pk_bf16_f32 v208, v20, v21
	v_cvt_pk_bf16_f32 v209, v22, v23
	v_cvt_pk_bf16_f32 v212, v16, v17
	v_cvt_pk_bf16_f32 v213, v18, v19
	global_store_dwordx2 v177, v[200:201], s[48:49]
	global_store_dwordx2 v177, v[204:205], s[48:49] offset:32
	global_store_dwordx2 v177, v[208:209], s[48:49] offset:256
	global_store_dwordx2 v177, v[212:213], s[48:49] offset:288
.Ler_f5_o:
	s_cmp_eq_u32 s44, 0
	s_cbranch_scc1 .Ler_f5_n
	v_mul_f32_e32 v245, v52, v52
	v_mul_f32_e32 v246, v53, v53
	v_add_f32_e32 v236, v245, v246
	v_mul_f32_e32 v245, v54, v54
	v_mul_f32_e32 v246, v55, v55
	v_add_f32_e32 v236, v245, v236
	v_add_f32_e32 v236, v246, v236
	v_mul_f32_e32 v245, v48, v48
	v_mul_f32_e32 v246, v49, v49
	v_add_f32_e32 v237, v245, v246
	v_mul_f32_e32 v245, v50, v50
	v_mul_f32_e32 v246, v51, v51
	v_add_f32_e32 v237, v245, v237
	v_add_f32_e32 v237, v246, v237
	v_add_f32_e32 v244, v236, v237
	v_mul_f32_e32 v245, v20, v20
	v_mul_f32_e32 v246, v21, v21
	v_add_f32_e32 v236, v245, v246
	v_mul_f32_e32 v245, v22, v22
	v_mul_f32_e32 v246, v23, v23
	v_add_f32_e32 v236, v245, v236
	v_add_f32_e32 v236, v246, v236
	v_add_f32_e32 v244, v244, v236
	v_mul_f32_e32 v245, v16, v16
	v_mul_f32_e32 v246, v17, v17
	v_add_f32_e32 v237, v245, v246
	v_mul_f32_e32 v245, v18, v18
	v_mul_f32_e32 v246, v19, v19
	v_add_f32_e32 v237, v245, v237
	v_add_f32_e32 v237, v246, v237
	v_add_f32_e32 v244, v244, v237
	ds_bpermute_b32 v247, v175, v244
	s_waitcnt lgkmcnt(0)
	v_add_f32_e32 v244, v244, v247
	ds_bpermute_b32 v247, v176, v244
	s_waitcnt lgkmcnt(0)
	s_and_saveexec_b64 s[0:1], s[36:37]
	v_add_f32_e32 v244, v244, v247
	global_atomic_add_f32 v174, v244, s[2:3] offset:576
	s_mov_b64 exec, s[0:1]
.Ler_f5_n:
	s_waitcnt vmcnt(16)
	v_add_f32_e32 v44, v44, v216
	v_add_f32_e32 v45, v45, v217
	v_add_f32_e32 v46, v46, v218
	v_add_f32_e32 v47, v47, v219
	v_add_f32_e32 v40, v40, v220
	v_add_f32_e32 v41, v41, v221
	v_add_f32_e32 v42, v42, v222
	v_add_f32_e32 v43, v43, v223
	v_add_f32_e32 v12, v12, v128
	v_add_f32_e32 v13, v13, v129
	v_add_f32_e32 v14, v14, v130
	v_add_f32_e32 v15, v15, v131
	v_add_f32_e32 v8, v8, v132
	v_add_f32_e32 v9, v9, v133
	v_add_f32_e32 v10, v10, v134
	v_add_f32_e32 v11, v11, v135
	s_cmp_eq_u32 s43, 0
	s_cbranch_scc1 .Ler_f6_b
	v_add_u32_e32 v177, 0xa0000, v172
	global_store_dwordx4 v177, v[44:47], s[94:95]
	global_store_dwordx4 v177, v[40:43], s[94:95] offset:64
	global_store_dwordx4 v177, v[12:15], s[94:95] offset:512
	global_store_dwordx4 v177, v[8:11], s[94:95] offset:576
	s_branch .Ler_f6_o
.Ler_f6_b:
	v_add_u32_e32 v177, 0x50000, v173
	v_cvt_pk_bf16_f32 v216, v44, v45
	v_cvt_pk_bf16_f32 v217, v46, v47
	v_cvt_pk_bf16_f32 v220, v40, v41
	v_cvt_pk_bf16_f32 v221, v42, v43
	v_cvt_pk_bf16_f32 v128, v12, v13
	v_cvt_pk_bf16_f32 v129, v14, v15
	v_cvt_pk_bf16_f32 v132, v8, v9
	v_cvt_pk_bf16_f32 v133, v10, v11
	global_store_dwordx2 v177, v[216:217], s[48:49]
	global_store_dwordx2 v177, v[220:221], s[48:49] offset:32
	global_store_dwordx2 v177, v[128:129], s[48:49] offset:256
	global_store_dwordx2 v177, v[132:133], s[48:49] offset:288
.Ler_f6_o:
	s_cmp_eq_u32 s44, 0
	s_cbranch_scc1 .Ler_f6_n
	v_mul_f32_e32 v245, v44, v44
	v_mul_f32_e32 v246, v45, v45
	v_add_f32_e32 v236, v245, v246
	v_mul_f32_e32 v245, v46, v46
	v_mul_f32_e32 v246, v47, v47
	v_add_f32_e32 v236, v245, v236
	v_add_f32_e32 v236, v246, v236
	v_mul_f32_e32 v245, v40, v40
	v_mul_f32_e32 v246, v41, v41
	v_add_f32_e32 v237, v245, v246
	v_mul_f32_e32 v245, v42, v42
	v_mul_f32_e32 v246, v43, v43
	v_add_f32_e32 v237, v245, v237
	v_add_f32_e32 v237, v246, v237
	v_add_f32_e32 v244, v236, v237
	v_mul_f32_e32 v245, v12, v12
	v_mul_f32_e32 v246, v13, v13
	v_add_f32_e32 v236, v245, v246
	v_mul_f32_e32 v245, v14, v14
	v_mul_f32_e32 v246, v15, v15
	v_add_f32_e32 v236, v245, v236
	v_add_f32_e32 v236, v246, v236
	v_add_f32_e32 v244, v244, v236
	v_mul_f32_e32 v245, v8, v8
	v_mul_f32_e32 v246, v9, v9
	v_add_f32_e32 v237, v245, v246
	v_mul_f32_e32 v245, v10, v10
	v_mul_f32_e32 v246, v11, v11
	v_add_f32_e32 v237, v245, v237
	v_add_f32_e32 v237, v246, v237
	v_add_f32_e32 v244, v244, v237
	ds_bpermute_b32 v247, v175, v244
	s_waitcnt lgkmcnt(0)
	v_add_f32_e32 v244, v244, v247
	ds_bpermute_b32 v247, v176, v244
	s_waitcnt lgkmcnt(0)
	s_and_saveexec_b64 s[0:1], s[36:37]
	v_add_f32_e32 v244, v244, v247
	global_atomic_add_f32 v174, v244, s[2:3] offset:640
	s_mov_b64 exec, s[0:1]
.Ler_f6_n:
	s_waitcnt vmcnt(12)
	v_add_f32_e32 v36, v36, v136
	v_add_f32_e32 v37, v37, v137
	v_add_f32_e32 v38, v38, v138
	v_add_f32_e32 v39, v39, v139
	v_add_f32_e32 v32, v32, v140
	v_add_f32_e32 v33, v33, v141
	v_add_f32_e32 v34, v34, v142
	v_add_f32_e32 v35, v35, v143
	v_add_f32_e32 v4, v4, v164
	v_add_f32_e32 v5, v5, v165
	v_add_f32_e32 v6, v6, v166
	v_add_f32_e32 v7, v7, v167
	v_add_f32_e32 v0, v0, v168
	v_add_f32_e32 v1, v1, v169
	v_add_f32_e32 v2, v2, v170
	v_add_f32_e32 v3, v3, v171
	s_cmp_eq_u32 s43, 0
	s_cbranch_scc1 .Ler_f7_b
	v_add_u32_e32 v177, 0xb0000, v172
	global_store_dwordx4 v177, v[36:39], s[94:95]
	global_store_dwordx4 v177, v[32:35], s[94:95] offset:64
	global_store_dwordx4 v177, v[4:7], s[94:95] offset:512
	global_store_dwordx4 v177, v[0:3], s[94:95] offset:576
	s_branch .Ler_f7_o
.Ler_f7_b:
	v_add_u32_e32 v177, 0x58000, v173
	v_cvt_pk_bf16_f32 v136, v36, v37
	v_cvt_pk_bf16_f32 v137, v38, v39
	v_cvt_pk_bf16_f32 v140, v32, v33
	v_cvt_pk_bf16_f32 v141, v34, v35
	v_cvt_pk_bf16_f32 v164, v4, v5
	v_cvt_pk_bf16_f32 v165, v6, v7
	v_cvt_pk_bf16_f32 v168, v0, v1
	v_cvt_pk_bf16_f32 v169, v2, v3
	global_store_dwordx2 v177, v[136:137], s[48:49]
	global_store_dwordx2 v177, v[140:141], s[48:49] offset:32
	global_store_dwordx2 v177, v[164:165], s[48:49] offset:256
	global_store_dwordx2 v177, v[168:169], s[48:49] offset:288
.Ler_f7_o:
	s_cmp_eq_u32 s44, 0
	s_cbranch_scc1 .Ler_f7_n
	v_mul_f32_e32 v245, v36, v36
	v_mul_f32_e32 v246, v37, v37
	v_add_f32_e32 v236, v245, v246
	v_mul_f32_e32 v245, v38, v38
	v_mul_f32_e32 v246, v39, v39
	v_add_f32_e32 v236, v245, v236
	v_add_f32_e32 v236, v246, v236
	v_mul_f32_e32 v245, v32, v32
	v_mul_f32_e32 v246, v33, v33
	v_add_f32_e32 v237, v245, v246
	v_mul_f32_e32 v245, v34, v34
	v_mul_f32_e32 v246, v35, v35
	v_add_f32_e32 v237, v245, v237
	v_add_f32_e32 v237, v246, v237
	v_add_f32_e32 v244, v236, v237
	v_mul_f32_e32 v245, v4, v4
	v_mul_f32_e32 v246, v5, v5
	v_add_f32_e32 v236, v245, v246
	v_mul_f32_e32 v245, v6, v6
	v_mul_f32_e32 v246, v7, v7
	v_add_f32_e32 v236, v245, v236
	v_add_f32_e32 v236, v246, v236
	v_add_f32_e32 v244, v244, v236
	v_mul_f32_e32 v245, v0, v0
	v_mul_f32_e32 v246, v1, v1
	v_add_f32_e32 v237, v245, v246
	v_mul_f32_e32 v245, v2, v2
	v_mul_f32_e32 v246, v3, v3
	v_add_f32_e32 v237, v245, v237
	v_add_f32_e32 v237, v246, v237
	v_add_f32_e32 v244, v244, v237
	ds_bpermute_b32 v247, v175, v244
	s_waitcnt lgkmcnt(0)
	v_add_f32_e32 v244, v244, v247
	ds_bpermute_b32 v247, v176, v244
	s_waitcnt lgkmcnt(0)
	s_and_saveexec_b64 s[0:1], s[36:37]
	v_add_f32_e32 v244, v244, v247
	global_atomic_add_f32 v174, v244, s[2:3] offset:704
	s_mov_b64 exec, s[0:1]

.Ler_bf:
	v_add_u32_e32 v177, 0x0, v173
	global_load_dwordx2 v[184:185], v177, s[48:49]
	global_load_dwordx2 v[186:187], v177, s[48:49] offset:32
	global_load_dwordx2 v[188:189], v177, s[48:49] offset:256
	global_load_dwordx2 v[190:191], v177, s[48:49] offset:288
	v_add_u32_e32 v177, 0x8000, v173
	global_load_dwordx2 v[192:193], v177, s[48:49]
	global_load_dwordx2 v[194:195], v177, s[48:49] offset:32
	global_load_dwordx2 v[196:197], v177, s[48:49] offset:256
	global_load_dwordx2 v[198:199], v177, s[48:49] offset:288
	v_add_u32_e32 v177, 0x10000, v173
	global_load_dwordx2 v[200:201], v177, s[48:49]
	global_load_dwordx2 v[202:203], v177, s[48:49] offset:32
	global_load_dwordx2 v[204:205], v177, s[48:49] offset:256
	global_load_dwordx2 v[206:207], v177, s[48:49] offset:288
	v_add_u32_e32 v177, 0x18000, v173
	global_load_dwordx2 v[208:209], v177, s[48:49]
	global_load_dwordx2 v[210:211], v177, s[48:49] offset:32
	global_load_dwordx2 v[212:213], v177, s[48:49] offset:256
	global_load_dwordx2 v[214:215], v177, s[48:49] offset:288
	v_add_u32_e32 v177, 0x40000, v173
	global_load_dwordx2 v[216:217], v177, s[48:49]
	global_load_dwordx2 v[218:219], v177, s[48:49] offset:32
	global_load_dwordx2 v[220:221], v177, s[48:49] offset:256
	global_load_dwordx2 v[222:223], v177, s[48:49] offset:288
	v_add_u32_e32 v177, 0x48000, v173
	global_load_dwordx2 v[128:129], v177, s[48:49]
	global_load_dwordx2 v[130:131], v177, s[48:49] offset:32
	global_load_dwordx2 v[132:133], v177, s[48:49] offset:256
	global_load_dwordx2 v[134:135], v177, s[48:49] offset:288
	v_add_u32_e32 v177, 0x50000, v173
	global_load_dwordx2 v[136:137], v177, s[48:49]
	global_load_dwordx2 v[138:139], v177, s[48:49] offset:32
	global_load_dwordx2 v[140:141], v177, s[48:49] offset:256
	global_load_dwordx2 v[142:143], v177, s[48:49] offset:288
	v_add_u32_e32 v177, 0x58000, v173
	global_load_dwordx2 v[164:165], v177, s[48:49]
	global_load_dwordx2 v[166:167], v177, s[48:49] offset:32
	global_load_dwordx2 v[168:169], v177, s[48:49] offset:256
	global_load_dwordx2 v[170:171], v177, s[48:49] offset:288
	s_waitcnt vmcnt(28)
	v_lshlrev_b32_e32 v232, 16, v184
	v_and_b32_e32 v233, 0xffff0000, v184
	v_lshlrev_b32_e32 v234, 16, v185
	v_and_b32_e32 v235, 0xffff0000, v185
	v_add_f32_e32 v124, v124, v232
	v_add_f32_e32 v125, v125, v233
	v_add_f32_e32 v126, v126, v234
	v_add_f32_e32 v127, v127, v235
	v_lshlrev_b32_e32 v232, 16, v186
	v_and_b32_e32 v233, 0xffff0000, v186
	v_lshlrev_b32_e32 v234, 16, v187
	v_and_b32_e32 v235, 0xffff0000, v187
	v_add_f32_e32 v120, v120, v232
	v_add_f32_e32 v121, v121, v233
	v_add_f32_e32 v122, v122, v234
	v_add_f32_e32 v123, v123, v235
	v_lshlrev_b32_e32 v232, 16, v188
	v_and_b32_e32 v233, 0xffff0000, v188
	v_lshlrev_b32_e32 v234, 16, v189
	v_and_b32_e32 v235, 0xffff0000, v189
	v_add_f32_e32 v92, v92, v232
	v_add_f32_e32 v93, v93, v233
	v_add_f32_e32 v94, v94, v234
	v_add_f32_e32 v95, v95, v235
	v_lshlrev_b32_e32 v232, 16, v190
	v_and_b32_e32 v233, 0xffff0000, v190
	v_lshlrev_b32_e32 v234, 16, v191
	v_and_b32_e32 v235, 0xffff0000, v191
	v_add_f32_e32 v88, v88, v232
	v_add_f32_e32 v89, v89, v233
	v_add_f32_e32 v90, v90, v234
	v_add_f32_e32 v91, v91, v235
	s_cmp_eq_u32 s43, 0
	s_cbranch_scc1 .Ler_h0_b
	v_add_u32_e32 v177, 0x0, v172
	global_store_dwordx4 v177, v[124:127], s[94:95]
	global_store_dwordx4 v177, v[120:123], s[94:95] offset:64
	global_store_dwordx4 v177, v[92:95], s[94:95] offset:512
	global_store_dwordx4 v177, v[88:91], s[94:95] offset:576
	s_branch .Ler_h0_o
.Ler_h0_b:
	v_add_u32_e32 v177, 0x0, v173
	v_cvt_pk_bf16_f32 v184, v124, v125
	v_cvt_pk_bf16_f32 v185, v126, v127
	v_cvt_pk_bf16_f32 v186, v120, v121
	v_cvt_pk_bf16_f32 v187, v122, v123
	v_cvt_pk_bf16_f32 v188, v92, v93
	v_cvt_pk_bf16_f32 v189, v94, v95
	v_cvt_pk_bf16_f32 v190, v88, v89
	v_cvt_pk_bf16_f32 v191, v90, v91
	global_store_dwordx2 v177, v[184:185], s[48:49]
	global_store_dwordx2 v177, v[186:187], s[48:49] offset:32
	global_store_dwordx2 v177, v[188:189], s[48:49] offset:256
	global_store_dwordx2 v177, v[190:191], s[48:49] offset:288

.Ler_h0_n:
	s_waitcnt vmcnt(28)
	v_lshlrev_b32_e32 v232, 16, v192
	v_and_b32_e32 v233, 0xffff0000, v192
	v_lshlrev_b32_e32 v234, 16, v193
	v_and_b32_e32 v235, 0xffff0000, v193
	v_add_f32_e32 v116, v116, v232
	v_add_f32_e32 v117, v117, v233
	v_add_f32_e32 v118, v118, v234
	v_add_f32_e32 v119, v119, v235
	v_lshlrev_b32_e32 v232, 16, v194
	v_and_b32_e32 v233, 0xffff0000, v194
	v_lshlrev_b32_e32 v234, 16, v195
	v_and_b32_e32 v235, 0xffff0000, v195
	v_add_f32_e32 v112, v112, v232
	v_add_f32_e32 v113, v113, v233
	v_add_f32_e32 v114, v114, v234
	v_add_f32_e32 v115, v115, v235
	v_lshlrev_b32_e32 v232, 16, v196
	v_and_b32_e32 v233, 0xffff0000, v196
	v_lshlrev_b32_e32 v234, 16, v197
	v_and_b32_e32 v235, 0xffff0000, v197
	v_add_f32_e32 v84, v84, v232
	v_add_f32_e32 v85, v85, v233
	v_add_f32_e32 v86, v86, v234
	v_add_f32_e32 v87, v87, v235
	v_lshlrev_b32_e32 v232, 16, v198
	v_and_b32_e32 v233, 0xffff0000, v198
	v_lshlrev_b32_e32 v234, 16, v199
	v_and_b32_e32 v235, 0xffff0000, v199
	v_add_f32_e32 v80, v80, v232
	v_add_f32_e32 v81, v81, v233
	v_add_f32_e32 v82, v82, v234
	v_add_f32_e32 v83, v83, v235
	s_cmp_eq_u32 s43, 0
	s_cbranch_scc1 .Ler_h1_b
	v_add_u32_e32 v177, 0x10000, v172
	global_store_dwordx4 v177, v[116:119], s[94:95]
	global_store_dwordx4 v177, v[112:115], s[94:95] offset:64
	global_store_dwordx4 v177, v[84:87], s[94:95] offset:512
	global_store_dwordx4 v177, v[80:83], s[94:95] offset:576
	s_branch .Ler_h1_o
.Ler_h1_b:
	v_add_u32_e32 v177, 0x8000, v173
	v_cvt_pk_bf16_f32 v192, v116, v117
	v_cvt_pk_bf16_f32 v193, v118, v119
	v_cvt_pk_bf16_f32 v194, v112, v113
	v_cvt_pk_bf16_f32 v195, v114, v115
	v_cvt_pk_bf16_f32 v196, v84, v85
	v_cvt_pk_bf16_f32 v197, v86, v87
	v_cvt_pk_bf16_f32 v198, v80, v81
	v_cvt_pk_bf16_f32 v199, v82, v83
	global_store_dwordx2 v177, v[192:193], s[48:49]
	global_store_dwordx2 v177, v[194:195], s[48:49] offset:32
	global_store_dwordx2 v177, v[196:197], s[48:49] offset:256
	global_store_dwordx2 v177, v[198:199], s[48:49] offset:288

.Ler_h1_n:
	s_waitcnt vmcnt(28)
	v_lshlrev_b32_e32 v232, 16, v200
	v_and_b32_e32 v233, 0xffff0000, v200
	v_lshlrev_b32_e32 v234, 16, v201
	v_and_b32_e32 v235, 0xffff0000, v201
	v_add_f32_e32 v108, v108, v232
	v_add_f32_e32 v109, v109, v233
	v_add_f32_e32 v110, v110, v234
	v_add_f32_e32 v111, v111, v235
	v_lshlrev_b32_e32 v232, 16, v202
	v_and_b32_e32 v233, 0xffff0000, v202
	v_lshlrev_b32_e32 v234, 16, v203
	v_and_b32_e32 v235, 0xffff0000, v203
	v_add_f32_e32 v104, v104, v232
	v_add_f32_e32 v105, v105, v233
	v_add_f32_e32 v106, v106, v234
	v_add_f32_e32 v107, v107, v235
	v_lshlrev_b32_e32 v232, 16, v204
	v_and_b32_e32 v233, 0xffff0000, v204
	v_lshlrev_b32_e32 v234, 16, v205
	v_and_b32_e32 v235, 0xffff0000, v205
	v_add_f32_e32 v76, v76, v232
	v_add_f32_e32 v77, v77, v233
	v_add_f32_e32 v78, v78, v234
	v_add_f32_e32 v79, v79, v235
	v_lshlrev_b32_e32 v232, 16, v206
	v_and_b32_e32 v233, 0xffff0000, v206
	v_lshlrev_b32_e32 v234, 16, v207
	v_and_b32_e32 v235, 0xffff0000, v207
	v_add_f32_e32 v72, v72, v232
	v_add_f32_e32 v73, v73, v233
	v_add_f32_e32 v74, v74, v234
	v_add_f32_e32 v75, v75, v235
	s_cmp_eq_u32 s43, 0
	s_cbranch_scc1 .Ler_h2_b
	v_add_u32_e32 v177, 0x20000, v172
	global_store_dwordx4 v177, v[108:111], s[94:95]
	global_store_dwordx4 v177, v[104:107], s[94:95] offset:64
	global_store_dwordx4 v177, v[76:79], s[94:95] offset:512
	global_store_dwordx4 v177, v[72:75], s[94:95] offset:576
	s_branch .Ler_h2_o
.Ler_h2_b:
	v_add_u32_e32 v177, 0x10000, v173
	v_cvt_pk_bf16_f32 v200, v108, v109
	v_cvt_pk_bf16_f32 v201, v110, v111
	v_cvt_pk_bf16_f32 v202, v104, v105
	v_cvt_pk_bf16_f32 v203, v106, v107
	v_cvt_pk_bf16_f32 v204, v76, v77
	v_cvt_pk_bf16_f32 v205, v78, v79
	v_cvt_pk_bf16_f32 v206, v72, v73
	v_cvt_pk_bf16_f32 v207, v74, v75
	global_store_dwordx2 v177, v[200:201], s[48:49]
	global_store_dwordx2 v177, v[202:203], s[48:49] offset:32
	global_store_dwordx2 v177, v[204:205], s[48:49] offset:256
	global_store_dwordx2 v177, v[206:207], s[48:49] offset:288

.Ler_h2_n:
	s_waitcnt vmcnt(28)
	v_lshlrev_b32_e32 v232, 16, v208
	v_and_b32_e32 v233, 0xffff0000, v208
	v_lshlrev_b32_e32 v234, 16, v209
	v_and_b32_e32 v235, 0xffff0000, v209
	v_add_f32_e32 v100, v100, v232
	v_add_f32_e32 v101, v101, v233
	v_add_f32_e32 v102, v102, v234
	v_add_f32_e32 v103, v103, v235
	v_lshlrev_b32_e32 v232, 16, v210
	v_and_b32_e32 v233, 0xffff0000, v210
	v_lshlrev_b32_e32 v234, 16, v211
	v_and_b32_e32 v235, 0xffff0000, v211
	v_add_f32_e32 v96, v96, v232
	v_add_f32_e32 v97, v97, v233
	v_add_f32_e32 v98, v98, v234
	v_add_f32_e32 v99, v99, v235
	v_lshlrev_b32_e32 v232, 16, v212
	v_and_b32_e32 v233, 0xffff0000, v212
	v_lshlrev_b32_e32 v234, 16, v213
	v_and_b32_e32 v235, 0xffff0000, v213
	v_add_f32_e32 v68, v68, v232
	v_add_f32_e32 v69, v69, v233
	v_add_f32_e32 v70, v70, v234
	v_add_f32_e32 v71, v71, v235
	v_lshlrev_b32_e32 v232, 16, v214
	v_and_b32_e32 v233, 0xffff0000, v214
	v_lshlrev_b32_e32 v234, 16, v215
	v_and_b32_e32 v235, 0xffff0000, v215
	v_add_f32_e32 v64, v64, v232
	v_add_f32_e32 v65, v65, v233
	v_add_f32_e32 v66, v66, v234
	v_add_f32_e32 v67, v67, v235
	s_cmp_eq_u32 s43, 0
	s_cbranch_scc1 .Ler_h3_b
	v_add_u32_e32 v177, 0x30000, v172
	global_store_dwordx4 v177, v[100:103], s[94:95]
	global_store_dwordx4 v177, v[96:99], s[94:95] offset:64
	global_store_dwordx4 v177, v[68:71], s[94:95] offset:512
	global_store_dwordx4 v177, v[64:67], s[94:95] offset:576
	s_branch .Ler_h3_o
.Ler_h3_b:
	v_add_u32_e32 v177, 0x18000, v173
	v_cvt_pk_bf16_f32 v208, v100, v101
	v_cvt_pk_bf16_f32 v209, v102, v103
	v_cvt_pk_bf16_f32 v210, v96, v97
	v_cvt_pk_bf16_f32 v211, v98, v99
	v_cvt_pk_bf16_f32 v212, v68, v69
	v_cvt_pk_bf16_f32 v213, v70, v71
	v_cvt_pk_bf16_f32 v214, v64, v65
	v_cvt_pk_bf16_f32 v215, v66, v67
	global_store_dwordx2 v177, v[208:209], s[48:49]
	global_store_dwordx2 v177, v[210:211], s[48:49] offset:32
	global_store_dwordx2 v177, v[212:213], s[48:49] offset:256
	global_store_dwordx2 v177, v[214:215], s[48:49] offset:288

.Ler_h3_n:
	s_waitcnt vmcnt(28)
	v_lshlrev_b32_e32 v232, 16, v216
	v_and_b32_e32 v233, 0xffff0000, v216
	v_lshlrev_b32_e32 v234, 16, v217
	v_and_b32_e32 v235, 0xffff0000, v217
	v_add_f32_e32 v60, v60, v232
	v_add_f32_e32 v61, v61, v233
	v_add_f32_e32 v62, v62, v234
	v_add_f32_e32 v63, v63, v235
	v_lshlrev_b32_e32 v232, 16, v218
	v_and_b32_e32 v233, 0xffff0000, v218
	v_lshlrev_b32_e32 v234, 16, v219
	v_and_b32_e32 v235, 0xffff0000, v219
	v_add_f32_e32 v56, v56, v232
	v_add_f32_e32 v57, v57, v233
	v_add_f32_e32 v58, v58, v234
	v_add_f32_e32 v59, v59, v235
	v_lshlrev_b32_e32 v232, 16, v220
	v_and_b32_e32 v233, 0xffff0000, v220
	v_lshlrev_b32_e32 v234, 16, v221
	v_and_b32_e32 v235, 0xffff0000, v221
	v_add_f32_e32 v28, v28, v232
	v_add_f32_e32 v29, v29, v233
	v_add_f32_e32 v30, v30, v234
	v_add_f32_e32 v31, v31, v235
	v_lshlrev_b32_e32 v232, 16, v222
	v_and_b32_e32 v233, 0xffff0000, v222
	v_lshlrev_b32_e32 v234, 16, v223
	v_and_b32_e32 v235, 0xffff0000, v223
	v_add_f32_e32 v24, v24, v232
	v_add_f32_e32 v25, v25, v233
	v_add_f32_e32 v26, v26, v234
	v_add_f32_e32 v27, v27, v235
	s_cmp_eq_u32 s43, 0
	s_cbranch_scc1 .Ler_h4_b
	v_add_u32_e32 v177, 0x80000, v172
	global_store_dwordx4 v177, v[60:63], s[94:95]
	global_store_dwordx4 v177, v[56:59], s[94:95] offset:64
	global_store_dwordx4 v177, v[28:31], s[94:95] offset:512
	global_store_dwordx4 v177, v[24:27], s[94:95] offset:576
	s_branch .Ler_h4_o
.Ler_h4_b:
	v_add_u32_e32 v177, 0x40000, v173
	v_cvt_pk_bf16_f32 v216, v60, v61
	v_cvt_pk_bf16_f32 v217, v62, v63
	v_cvt_pk_bf16_f32 v218, v56, v57
	v_cvt_pk_bf16_f32 v219, v58, v59
	v_cvt_pk_bf16_f32 v220, v28, v29
	v_cvt_pk_bf16_f32 v221, v30, v31
	v_cvt_pk_bf16_f32 v222, v24, v25
	v_cvt_pk_bf16_f32 v223, v26, v27
	global_store_dwordx2 v177, v[216:217], s[48:49]
	global_store_dwordx2 v177, v[218:219], s[48:49] offset:32
	global_store_dwordx2 v177, v[220:221], s[48:49] offset:256
	global_store_dwordx2 v177, v[222:223], s[48:49] offset:288

.Ler_h4_n:
	s_waitcnt vmcnt(28)
	v_lshlrev_b32_e32 v232, 16, v128
	v_and_b32_e32 v233, 0xffff0000, v128
	v_lshlrev_b32_e32 v234, 16, v129
	v_and_b32_e32 v235, 0xffff0000, v129
	v_add_f32_e32 v52, v52, v232
	v_add_f32_e32 v53, v53, v233
	v_add_f32_e32 v54, v54, v234
	v_add_f32_e32 v55, v55, v235
	v_lshlrev_b32_e32 v232, 16, v130
	v_and_b32_e32 v233, 0xffff0000, v130
	v_lshlrev_b32_e32 v234, 16, v131
	v_and_b32_e32 v235, 0xffff0000, v131
	v_add_f32_e32 v48, v48, v232
	v_add_f32_e32 v49, v49, v233
	v_add_f32_e32 v50, v50, v234
	v_add_f32_e32 v51, v51, v235
	v_lshlrev_b32_e32 v232, 16, v132
	v_and_b32_e32 v233, 0xffff0000, v132
	v_lshlrev_b32_e32 v234, 16, v133
	v_and_b32_e32 v235, 0xffff0000, v133
	v_add_f32_e32 v20, v20, v232
	v_add_f32_e32 v21, v21, v233
	v_add_f32_e32 v22, v22, v234
	v_add_f32_e32 v23, v23, v235
	v_lshlrev_b32_e32 v232, 16, v134
	v_and_b32_e32 v233, 0xffff0000, v134
	v_lshlrev_b32_e32 v234, 16, v135
	v_and_b32_e32 v235, 0xffff0000, v135
	v_add_f32_e32 v16, v16, v232
	v_add_f32_e32 v17, v17, v233
	v_add_f32_e32 v18, v18, v234
	v_add_f32_e32 v19, v19, v235
	s_cmp_eq_u32 s43, 0
	s_cbranch_scc1 .Ler_h5_b
	v_add_u32_e32 v177, 0x90000, v172
	global_store_dwordx4 v177, v[52:55], s[94:95]
	global_store_dwordx4 v177, v[48:51], s[94:95] offset:64
	global_store_dwordx4 v177, v[20:23], s[94:95] offset:512
	global_store_dwordx4 v177, v[16:19], s[94:95] offset:576
	s_branch .Ler_h5_o
.Ler_h5_b:
	v_add_u32_e32 v177, 0x48000, v173
	v_cvt_pk_bf16_f32 v128, v52, v53
	v_cvt_pk_bf16_f32 v129, v54, v55
	v_cvt_pk_bf16_f32 v130, v48, v49
	v_cvt_pk_bf16_f32 v131, v50, v51
	v_cvt_pk_bf16_f32 v132, v20, v21
	v_cvt_pk_bf16_f32 v133, v22, v23
	v_cvt_pk_bf16_f32 v134, v16, v17
	v_cvt_pk_bf16_f32 v135, v18, v19
	global_store_dwordx2 v177, v[128:129], s[48:49]
	global_store_dwordx2 v177, v[130:131], s[48:49] offset:32
	global_store_dwordx2 v177, v[132:133], s[48:49] offset:256
	global_store_dwordx2 v177, v[134:135], s[48:49] offset:288

.Ler_h5_n:
	s_waitcnt vmcnt(28)
	v_lshlrev_b32_e32 v232, 16, v136
	v_and_b32_e32 v233, 0xffff0000, v136
	v_lshlrev_b32_e32 v234, 16, v137
	v_and_b32_e32 v235, 0xffff0000, v137
	v_add_f32_e32 v44, v44, v232
	v_add_f32_e32 v45, v45, v233
	v_add_f32_e32 v46, v46, v234
	v_add_f32_e32 v47, v47, v235
	v_lshlrev_b32_e32 v232, 16, v138
	v_and_b32_e32 v233, 0xffff0000, v138
	v_lshlrev_b32_e32 v234, 16, v139
	v_and_b32_e32 v235, 0xffff0000, v139
	v_add_f32_e32 v40, v40, v232
	v_add_f32_e32 v41, v41, v233
	v_add_f32_e32 v42, v42, v234
	v_add_f32_e32 v43, v43, v235
	v_lshlrev_b32_e32 v232, 16, v140
	v_and_b32_e32 v233, 0xffff0000, v140
	v_lshlrev_b32_e32 v234, 16, v141
	v_and_b32_e32 v235, 0xffff0000, v141
	v_add_f32_e32 v12, v12, v232
	v_add_f32_e32 v13, v13, v233
	v_add_f32_e32 v14, v14, v234
	v_add_f32_e32 v15, v15, v235
	v_lshlrev_b32_e32 v232, 16, v142
	v_and_b32_e32 v233, 0xffff0000, v142
	v_lshlrev_b32_e32 v234, 16, v143
	v_and_b32_e32 v235, 0xffff0000, v143
	v_add_f32_e32 v8, v8, v232
	v_add_f32_e32 v9, v9, v233
	v_add_f32_e32 v10, v10, v234
	v_add_f32_e32 v11, v11, v235
	s_cmp_eq_u32 s43, 0
	s_cbranch_scc1 .Ler_h6_b
	v_add_u32_e32 v177, 0xa0000, v172
	global_store_dwordx4 v177, v[44:47], s[94:95]
	global_store_dwordx4 v177, v[40:43], s[94:95] offset:64
	global_store_dwordx4 v177, v[12:15], s[94:95] offset:512
	global_store_dwordx4 v177, v[8:11], s[94:95] offset:576
	s_branch .Ler_h6_o
.Ler_h6_b:
	v_add_u32_e32 v177, 0x50000, v173
	v_cvt_pk_bf16_f32 v136, v44, v45
	v_cvt_pk_bf16_f32 v137, v46, v47
	v_cvt_pk_bf16_f32 v138, v40, v41
	v_cvt_pk_bf16_f32 v139, v42, v43
	v_cvt_pk_bf16_f32 v140, v12, v13
	v_cvt_pk_bf16_f32 v141, v14, v15
	v_cvt_pk_bf16_f32 v142, v8, v9
	v_cvt_pk_bf16_f32 v143, v10, v11
	global_store_dwordx2 v177, v[136:137], s[48:49]
	global_store_dwordx2 v177, v[138:139], s[48:49] offset:32
	global_store_dwordx2 v177, v[140:141], s[48:49] offset:256
	global_store_dwordx2 v177, v[142:143], s[48:49] offset:288

.Ler_h6_n:
	s_waitcnt vmcnt(28)
	v_lshlrev_b32_e32 v232, 16, v164
	v_and_b32_e32 v233, 0xffff0000, v164
	v_lshlrev_b32_e32 v234, 16, v165
	v_and_b32_e32 v235, 0xffff0000, v165
	v_add_f32_e32 v36, v36, v232
	v_add_f32_e32 v37, v37, v233
	v_add_f32_e32 v38, v38, v234
	v_add_f32_e32 v39, v39, v235
	v_lshlrev_b32_e32 v232, 16, v166
	v_and_b32_e32 v233, 0xffff0000, v166
	v_lshlrev_b32_e32 v234, 16, v167
	v_and_b32_e32 v235, 0xffff0000, v167
	v_add_f32_e32 v32, v32, v232
	v_add_f32_e32 v33, v33, v233
	v_add_f32_e32 v34, v34, v234
	v_add_f32_e32 v35, v35, v235
	v_lshlrev_b32_e32 v232, 16, v168
	v_and_b32_e32 v233, 0xffff0000, v168
	v_lshlrev_b32_e32 v234, 16, v169
	v_and_b32_e32 v235, 0xffff0000, v169
	v_add_f32_e32 v4, v4, v232
	v_add_f32_e32 v5, v5, v233
	v_add_f32_e32 v6, v6, v234
	v_add_f32_e32 v7, v7, v235
	v_lshlrev_b32_e32 v232, 16, v170
	v_and_b32_e32 v233, 0xffff0000, v170
	v_lshlrev_b32_e32 v234, 16, v171
	v_and_b32_e32 v235, 0xffff0000, v171
	v_add_f32_e32 v0, v0, v232
	v_add_f32_e32 v1, v1, v233
	v_add_f32_e32 v2, v2, v234
	v_add_f32_e32 v3, v3, v235
	s_cmp_eq_u32 s43, 0
	s_cbranch_scc1 .Ler_h7_b
	v_add_u32_e32 v177, 0xb0000, v172
	global_store_dwordx4 v177, v[36:39], s[94:95]
	global_store_dwordx4 v177, v[32:35], s[94:95] offset:64
	global_store_dwordx4 v177, v[4:7], s[94:95] offset:512
	global_store_dwordx4 v177, v[0:3], s[94:95] offset:576
	s_branch .Ler_h7_o
.Ler_h7_b:
	v_add_u32_e32 v177, 0x58000, v173
	v_cvt_pk_bf16_f32 v164, v36, v37
	v_cvt_pk_bf16_f32 v165, v38, v39
	v_cvt_pk_bf16_f32 v166, v32, v33
	v_cvt_pk_bf16_f32 v167, v34, v35
	v_cvt_pk_bf16_f32 v168, v4, v5
	v_cvt_pk_bf16_f32 v169, v6, v7
	v_cvt_pk_bf16_f32 v170, v0, v1
	v_cvt_pk_bf16_f32 v171, v2, v3
	global_store_dwordx2 v177, v[164:165], s[48:49]
	global_store_dwordx2 v177, v[166:167], s[48:49] offset:32
	global_store_dwordx2 v177, v[168:169], s[48:49] offset:256
	global_store_dwordx2 v177, v[170:171], s[48:49] offset:288

.Ler_h7_n:
.Ler_done:
.LBB0_611:
	s_and_b64 vcc, exec, s[40:41]
	s_cbranch_vccnz .LBB0_114
	v_mov_b32_e32 v0, 0
	s_mov_b32 s72, s89
	s_mov_b32 s76, s90
	s_mov_b64 s[26:27], s[30:31]
	s_mov_b64 s[56:57], s[10:11]
	s_mov_b32 s51, s91
	v_mov_b32_e32 v1, v0
	v_mov_b32_e32 v2, v0
	v_mov_b32_e32 v3, v0
	v_mov_b32_e32 v4, v0
	v_mov_b32_e32 v5, v0
	v_mov_b32_e32 v6, v0
	v_mov_b32_e32 v7, v0
	v_mov_b32_e32 v8, v0
	v_mov_b32_e32 v9, v0
	v_mov_b32_e32 v10, v0
	v_mov_b32_e32 v11, v0
	v_mov_b32_e32 v12, v0
	v_mov_b32_e32 v13, v0
	v_mov_b32_e32 v14, v0
	v_mov_b32_e32 v15, v0
	v_mov_b32_e32 v16, v0
	v_mov_b32_e32 v17, v0
	v_mov_b32_e32 v18, v0
	v_mov_b32_e32 v19, v0
	v_mov_b32_e32 v20, v0
	v_mov_b32_e32 v21, v0
	v_mov_b32_e32 v22, v0
	v_mov_b32_e32 v23, v0
	v_mov_b32_e32 v24, v0
	v_mov_b32_e32 v25, v0
	v_mov_b32_e32 v26, v0
	v_mov_b32_e32 v27, v0
	v_mov_b32_e32 v28, v0
	v_mov_b32_e32 v29, v0
	v_mov_b32_e32 v30, v0
	v_mov_b32_e32 v31, v0
	v_mov_b32_e32 v32, v0
	v_mov_b32_e32 v33, v0
	v_mov_b32_e32 v34, v0
	v_mov_b32_e32 v35, v0
	v_mov_b32_e32 v36, v0
	v_mov_b32_e32 v37, v0
	v_mov_b32_e32 v38, v0
	v_mov_b32_e32 v39, v0
	v_mov_b32_e32 v40, v0
	v_mov_b32_e32 v41, v0
	v_mov_b32_e32 v42, v0
	v_mov_b32_e32 v43, v0
	v_mov_b32_e32 v44, v0
	v_mov_b32_e32 v45, v0
	v_mov_b32_e32 v46, v0
	v_mov_b32_e32 v47, v0
	v_mov_b32_e32 v48, v0
	v_mov_b32_e32 v49, v0
	v_mov_b32_e32 v50, v0
	v_mov_b32_e32 v51, v0
	v_mov_b32_e32 v52, v0
	v_mov_b32_e32 v53, v0
	v_mov_b32_e32 v54, v0
	v_mov_b32_e32 v55, v0
	v_mov_b32_e32 v56, v0
	v_mov_b32_e32 v57, v0
	v_mov_b32_e32 v58, v0
	v_mov_b32_e32 v59, v0
	v_mov_b32_e32 v60, v0
	v_mov_b32_e32 v61, v0
	v_mov_b32_e32 v62, v0
	v_mov_b32_e32 v63, v0
	v_mov_b32_e32 v64, v0
	v_mov_b32_e32 v65, v0
	v_mov_b32_e32 v66, v0
	v_mov_b32_e32 v67, v0
	v_mov_b32_e32 v68, v0
	v_mov_b32_e32 v69, v0
	v_mov_b32_e32 v70, v0
	v_mov_b32_e32 v71, v0
	v_mov_b32_e32 v72, v0
	v_mov_b32_e32 v73, v0
	v_mov_b32_e32 v74, v0
	v_mov_b32_e32 v75, v0
	v_mov_b32_e32 v76, v0
	v_mov_b32_e32 v77, v0
	v_mov_b32_e32 v78, v0
	v_mov_b32_e32 v79, v0
	v_mov_b32_e32 v80, v0
	v_mov_b32_e32 v81, v0
	v_mov_b32_e32 v82, v0
	v_mov_b32_e32 v83, v0
	v_mov_b32_e32 v84, v0
	v_mov_b32_e32 v85, v0
	v_mov_b32_e32 v86, v0
	v_mov_b32_e32 v87, v0
	v_mov_b32_e32 v88, v0
	v_mov_b32_e32 v89, v0
	v_mov_b32_e32 v90, v0
	v_mov_b32_e32 v91, v0
	v_mov_b32_e32 v92, v0
	v_mov_b32_e32 v93, v0
	v_mov_b32_e32 v94, v0
	v_mov_b32_e32 v95, v0
	v_mov_b32_e32 v96, v0
	v_mov_b32_e32 v97, v0
	v_mov_b32_e32 v98, v0
	v_mov_b32_e32 v99, v0
	v_mov_b32_e32 v100, v0
	v_mov_b32_e32 v101, v0
	v_mov_b32_e32 v102, v0
	v_mov_b32_e32 v103, v0
	v_mov_b32_e32 v104, v0
	v_mov_b32_e32 v105, v0
	v_mov_b32_e32 v106, v0
	v_mov_b32_e32 v107, v0
	v_mov_b32_e32 v108, v0
	v_mov_b32_e32 v109, v0
	v_mov_b32_e32 v110, v0
	v_mov_b32_e32 v111, v0
	v_mov_b32_e32 v112, v0
	v_mov_b32_e32 v113, v0
	v_mov_b32_e32 v114, v0
	v_mov_b32_e32 v115, v0
	v_mov_b32_e32 v116, v0
	v_mov_b32_e32 v117, v0
	v_mov_b32_e32 v118, v0
	v_mov_b32_e32 v119, v0
	v_mov_b32_e32 v120, v0
	v_mov_b32_e32 v121, v0
	v_mov_b32_e32 v122, v0
	v_mov_b32_e32 v123, v0
	v_mov_b32_e32 v124, v0
	v_mov_b32_e32 v125, v0
	v_mov_b32_e32 v126, v0
	v_mov_b32_e32 v127, v0
	s_branch .LBB0_114
